# NSA selected loop: V fragments read once per tile and shared by the column groups; P.V section without interleaved LDS reads
# speedup vs baseline: 1.0307x; 1.0097x over previous
; __device__ __forceinline__ float xmax16(float v) { const auto r = __builtin_amdgcn_permlane16_swap(__float_as_uint(v), __float_as_uint(v), false, false); return fmaxf(__uint_as_float(r[0]), __uint_as_float(r[1])); }
; __device__ __forceinline__ float xmax32(float v) { const auto r = __builtin_amdgcn_permlane32_swap(__float_as_uint(v), __float_as_uint(v), false, false); return fmaxf(__uint_as_float(r[0]), __uint_as_float(r[1])); }
; #define LAS __attribute__((address_space(3)))
; __device__ __forceinline__ s16x4 vtr(const LAS bf16_t* p) { return __builtin_bit_cast(s16x4, __builtin_amdgcn_ds_read_tr16_b64_v4i16((LAS v4i16_t*)p)); }
; __device__ __forceinline__ void sel_group(const LAS bf16_t* Kt, const LAS bf16_t* Vt, LAS float* S, const bf16x8 qB0, const bf16x8 qB1, int jc, int rc, bool valid, bool masked, int tw64, int lr, int q) {
;     ...
;     float mx = fmaxf(fmaxf(fmaxf(fmaxf(fmaxf(s[0][0], s[0][1]), s[0][2]), fmaxf(fmaxf(s[0][3], s[1][0]), s[1][1])), fmaxf(fmaxf(s[1][2], s[1][3]), s[2][0])), fmaxf(fmaxf(fmaxf(fmaxf(s[2][1], s[2][2]), s[2][3]), fmaxf(fmaxf(s[3][0], s[3][1]), s[3][2])), s[3][3]));
;     mx = pg8::xmax16(mx); mx = pg8::xmax32(mx);
;     const bool need = valid && (mx > -1e29f) && (!st || mx > RESC_THR);
;     const bool anyneed = __builtin_amdgcn_ballot_w64(need) != 0ull;
;     float alpha = 1.f;
;     if (anyneed) {
;         const float dl = need ? mx : 0.f;
;         alpha = need ? (st ? __builtin_amdgcn_exp2f(-dl) : 0.f) : 1.f;
; #pragma unroll
;         for (int mt = 0; mt < 4; ++mt) s[mt] = s[mt] - dl;
;         if (need && q == 0) { Srow[65] = mref + dl; Srow[66] = 1.f; }
;     }
;     ...
;         const LAS bf16_t* vbase = Vt + (4 * q + (lr >> 2)) * 72 + 4 * (lr & 3);
;         const bf16x8 ones = (bf16x8){0x3F80, 0x3F80, 0x3F80, 0x3F80, 0x3F80, 0x3F80, 0x3F80, 0x3F80};
;         s16x4 vv[2][2];
;         vv[0][0] = vtr(vbase); vv[0][1] = vtr(vbase + 16 * 72);
; #pragma unroll
;         for (int it = 0; it < 8; ++it) {
;             const int kk = it >> 2, dt = it & 3;
;             if (it < 7) { const int kk2 = (it + 1) >> 2, dt2 = (it + 1) & 3; vv[(it + 1) & 1][0] = vtr(vbase + (32 * kk2) * 72 + 16 * dt2); vv[(it + 1) & 1][1] = vtr(vbase + (32 * kk2 + 16) * 72 + 16 * dt2); }
;             __builtin_amdgcn_sched_barrier(0);
.LBB0_1067:
	ds_read_b64_tr_b16 v[142:143], v115 offset:18432
	ds_read_b64_tr_b16 v[144:145], v115 offset:20736
	ds_read_b64_tr_b16 v[146:147], v115 offset:18464
	ds_read_b64_tr_b16 v[148:149], v115 offset:20768
	ds_read_b64_tr_b16 v[150:151], v115 offset:18496
	ds_read_b64_tr_b16 v[152:153], v115 offset:20800
	ds_read_b64_tr_b16 v[154:155], v115 offset:18528
	ds_read_b64_tr_b16 v[156:157], v115 offset:20832
	ds_read_b64_tr_b16 v[158:159], v115 offset:23040
	ds_read_b64_tr_b16 v[160:161], v115 offset:25344
	ds_read_b64_tr_b16 v[162:163], v115 offset:23072
	ds_read_b64_tr_b16 v[164:165], v115 offset:25376
	ds_read_b64_tr_b16 v[166:167], v115 offset:23104
	ds_read_b64_tr_b16 v[168:169], v115 offset:25408
	ds_read_b64_tr_b16 v[170:171], v115 offset:23136
	ds_read_b64_tr_b16 v[172:173], v115 offset:25440
	v_max_f32_e32 v80, v65, v65
	v_max_f32_e32 v81, v64, v64
	v_max_f32_e32 v80, v81, v80
	v_max3_f32 v81, v67, v68, v69
	v_max3_f32 v82, v73, v74, v75
	v_max3_f32 v83, v76, v77, v78
	v_max3_f32 v80, v80, v66, v81
	v_max3_f32 v81, v70, v71, v72
	v_max3_f32 v82, v82, v83, v79
	v_max3_f32 v80, v80, v81, v82
	v_mov_b32_e32 v81, v80
	s_nop 1
	v_permlane16_swap_b32_e32 v80, v81
	v_max_f32_e32 v81, v81, v81
	v_max_f32_e32 v80, v80, v80
	v_max_f32_e32 v80, v80, v81
	v_mov_b32_e32 v81, v80
	s_nop 1
	v_permlane32_swap_b32_e32 v80, v81
	v_max_f32_e32 v81, v81, v81
	v_max_f32_e32 v80, v80, v80
	v_max_f32_e32 v80, v80, v81
	v_cmp_lt_f32_e32 vcc, s33, v80
	v_cmp_eq_f32_e64 s[80:81], 0, v86
	s_and_b64 s[4:5], s[76:77], vcc
	v_cmp_lt_f32_e32 vcc, s88, v80
	s_or_b64 s[6:7], s[80:81], vcc
	s_and_b64 s[78:79], s[4:5], s[6:7]
	v_cndmask_b32_e64 v81, 0, 1, s[78:79]
	v_cmp_ne_u32_e32 vcc, 0, v81
	s_cmp_lg_u64 vcc, 0
	s_cselect_b64 s[4:5], -1, 0
	s_cbranch_vccz .LBB0_1071
	v_cndmask_b32_e64 v80, 0, v80, s[78:79]
	s_and_b64 s[12:13], s[68:69], s[78:79]
	s_and_saveexec_b64 s[6:7], s[12:13]
	v_add_f32_e32 v81, v85, v80
	v_add_u32_e32 v82, 0xb504, v119
	ds_write2_b32 v82, v81, v225 offset1:1
	s_or_b64 exec, exec, s[6:7]
	v_exp_f32_e64 v81, -v80
	v_sub_f32_e32 v79, v79, v80
	v_sub_f32_e32 v78, v78, v80
	v_sub_f32_e32 v77, v77, v80
	v_cndmask_b32_e64 v81, v81, 0, s[80:81]
	v_sub_f32_e32 v76, v76, v80
	v_sub_f32_e32 v75, v75, v80
	v_sub_f32_e32 v74, v74, v80
	v_sub_f32_e32 v73, v73, v80
	v_sub_f32_e32 v72, v72, v80
	v_sub_f32_e32 v71, v71, v80
	v_sub_f32_e32 v70, v70, v80
	v_sub_f32_e32 v69, v69, v80
	v_sub_f32_e32 v68, v68, v80
	v_sub_f32_e32 v67, v67, v80
	v_sub_f32_e32 v66, v66, v80
	v_sub_f32_e32 v65, v65, v80
	v_sub_f32_e32 v64, v64, v80
	v_cndmask_b32_e64 v80, 1.0, v81, s[78:79]
	s_branch .LBB0_1072

; #define LAS __attribute__((address_space(3)))
; __device__ __forceinline__ bf16x8 mk8(s16x4 a, s16x4 b) { return __builtin_shufflevector(a, b, 0, 1, 2, 3, 4, 5, 6, 7); }
; #define MFMA16(a, b, c) __builtin_amdgcn_mfma_f32_16x16x32_bf16((a), (b), (c), 0, 0, 0)
; __device__ __forceinline__ s16x4 vtr(const LAS bf16_t* p) { return __builtin_bit_cast(s16x4, __builtin_amdgcn_ds_read_tr16_b64_v4i16((LAS v4i16_t*)p)); }
; __device__ __forceinline__ void sel_group(const LAS bf16_t* Kt, const LAS bf16_t* Vt, LAS float* S, const bf16x8 qB0, const bf16x8 qB1, int jc, int rc, bool valid, bool masked, int tw64, int lr, int q) {
;     ...
;     f32x4 ls = (f32x4){0.f, 0.f, 0.f, 0.f};
;     {
;         const LAS bf16_t* vbase = Vt + (4 * q + (lr >> 2)) * 72 + 4 * (lr & 3);
;         const bf16x8 ones = (bf16x8){0x3F80, 0x3F80, 0x3F80, 0x3F80, 0x3F80, 0x3F80, 0x3F80, 0x3F80};
;         s16x4 vv[2][2];
;         vv[0][0] = vtr(vbase); vv[0][1] = vtr(vbase + 16 * 72);
; #pragma unroll
;         for (int it = 0; it < 8; ++it) {
;             const int kk = it >> 2, dt = it & 3;
;             if (it < 7) { const int kk2 = (it + 1) >> 2, dt2 = (it + 1) & 3; vv[(it + 1) & 1][0] = vtr(vbase + (32 * kk2) * 72 + 16 * dt2); vv[(it + 1) & 1][1] = vtr(vbase + (32 * kk2 + 16) * 72 + 16 * dt2); }
;             __builtin_amdgcn_sched_barrier(0);
;             const bf16x8 vf = mk8(vv[it & 1][0], vv[it & 1][1]);
;             __builtin_amdgcn_s_setprio(1); acc[dt] = MFMA16(vf, pb[kk], acc[dt]);
;             if (dt == 0) ls = MFMA16(ones, pb[kk], ls);
;             __builtin_amdgcn_s_setprio(0);
;             __builtin_amdgcn_sched_barrier(0);
;         }
;     }
;     if (valid) {
; #pragma unroll
;         for (int dt = 0; dt < 4; ++dt) *(LAS f32x4*)(Srow + 16 * dt + 4 * q) = acc[dt];
;         if (q == 0) Srow[64] = lc + ls[0];
;     }
.LBB0_1074:
	s_mov_b32 s18, s16
	s_mov_b32 s19, s16
	s_mov_b32 s17, s16
	v_mov_b64_e32 v[74:75], s[18:19]
	v_mov_b64_e32 v[72:73], s[16:17]
	s_waitcnt lgkmcnt(0)
	v_mfma_f32_16x16x32_bf16 v[60:63], v[142:145], v[68:71], v[60:63]
	s_nop 0
	v_mfma_f32_16x16x32_bf16 v[80:83], v[72:75], v[68:71], 0
	v_mfma_f32_16x16x32_bf16 v[56:59], v[146:149], v[68:71], v[56:59]
	v_mfma_f32_16x16x32_bf16 v[120:123], v[150:153], v[68:71], v[52:55]
	v_mfma_f32_16x16x32_bf16 v[68:71], v[154:157], v[68:71], v[48:51]
	v_mfma_f32_16x16x32_bf16 v[52:55], v[158:161], v[64:67], v[60:63]
	v_mfma_f32_16x16x32_bf16 v[48:51], v[72:75], v[64:67], v[80:83]
	v_mfma_f32_16x16x32_bf16 v[56:59], v[162:165], v[64:67], v[56:59]
	v_mfma_f32_16x16x32_bf16 v[60:63], v[166:169], v[64:67], v[120:123]
	v_mfma_f32_16x16x32_bf16 v[64:67], v[170:173], v[64:67], v[68:71]
	s_nop 2
	s_and_saveexec_b64 s[4:5], s[76:77]
	s_cbranch_execz .LBB0_1077
	v_lshl_add_u32 v49, v89, 2, v119
	ds_write_b128 v49, v[52:55] offset:46080
	ds_write_b128 v49, v[56:59] offset:46144
	ds_write_b128 v49, v[60:63] offset:46208
	s_nop 0
	ds_write_b128 v49, v[64:67] offset:46272
	s_and_b64 exec, exec, s[68:69]
	v_add_f32_e32 v48, v84, v48
	ds_write_b32 v119, v48 offset:46336

; #define LAS __attribute__((address_space(3)))
; __device__ __forceinline__ bf16x8 mk8(s16x4 a, s16x4 b) { return __builtin_shufflevector(a, b, 0, 1, 2, 3, 4, 5, 6, 7); }
; #define MFMA16(a, b, c) __builtin_amdgcn_mfma_f32_16x16x32_bf16((a), (b), (c), 0, 0, 0)
; __device__ __forceinline__ s16x4 vtr(const LAS bf16_t* p) { return __builtin_bit_cast(s16x4, __builtin_amdgcn_ds_read_tr16_b64_v4i16((LAS v4i16_t*)p)); }
; __device__ __forceinline__ void sel_group(const LAS bf16_t* Kt, const LAS bf16_t* Vt, LAS float* S, const bf16x8 qB0, const bf16x8 qB1, int jc, int rc, bool valid, bool masked, int tw64, int lr, int q) {
;     ...
;     f32x4 ls = (f32x4){0.f, 0.f, 0.f, 0.f};
;     {
;         const LAS bf16_t* vbase = Vt + (4 * q + (lr >> 2)) * 72 + 4 * (lr & 3);
;         const bf16x8 ones = (bf16x8){0x3F80, 0x3F80, 0x3F80, 0x3F80, 0x3F80, 0x3F80, 0x3F80, 0x3F80};
;         s16x4 vv[2][2];
;         vv[0][0] = vtr(vbase); vv[0][1] = vtr(vbase + 16 * 72);
; #pragma unroll
;         for (int it = 0; it < 8; ++it) {
;             const int kk = it >> 2, dt = it & 3;
;             if (it < 7) { const int kk2 = (it + 1) >> 2, dt2 = (it + 1) & 3; vv[(it + 1) & 1][0] = vtr(vbase + (32 * kk2) * 72 + 16 * dt2); vv[(it + 1) & 1][1] = vtr(vbase + (32 * kk2 + 16) * 72 + 16 * dt2); }
;             __builtin_amdgcn_sched_barrier(0);
;             const bf16x8 vf = mk8(vv[it & 1][0], vv[it & 1][1]);
;             __builtin_amdgcn_s_setprio(1); acc[dt] = MFMA16(vf, pb[kk], acc[dt]);
;             if (dt == 0) ls = MFMA16(ones, pb[kk], ls);
;             __builtin_amdgcn_s_setprio(0);
;             __builtin_amdgcn_sched_barrier(0);
;         }
;     }
;     if (valid) {
; #pragma unroll
;         for (int dt = 0; dt < 4; ++dt) *(LAS f32x4*)(Srow + 16 * dt + 4 * q) = acc[dt];
;         if (q == 0) Srow[64] = lc + ls[0];
;     }
.LBB0_1088:
	s_mov_b32 s18, s16
	s_mov_b32 s19, s16
	s_mov_b32 s17, s16
	v_mov_b64_e32 v[66:67], s[18:19]
	v_mov_b64_e32 v[64:65], s[16:17]
	s_waitcnt lgkmcnt(0)
	v_mfma_f32_16x16x32_bf16 v[60:63], v[142:145], v[44:47], v[60:63]
	s_nop 0
	v_mfma_f32_16x16x32_bf16 v[72:75], v[64:67], v[44:47], 0
	v_mfma_f32_16x16x32_bf16 v[56:59], v[146:149], v[44:47], v[56:59]
	v_mfma_f32_16x16x32_bf16 v[80:83], v[150:153], v[44:47], v[52:55]
	v_mfma_f32_16x16x32_bf16 v[68:71], v[154:157], v[44:47], v[48:51]
	v_mfma_f32_16x16x32_bf16 v[48:51], v[158:161], v[40:43], v[60:63]
	v_mfma_f32_16x16x32_bf16 v[44:47], v[64:67], v[40:43], v[72:75]
	v_mfma_f32_16x16x32_bf16 v[52:55], v[162:165], v[40:43], v[56:59]
	v_mfma_f32_16x16x32_bf16 v[56:59], v[166:169], v[40:43], v[80:83]
	v_mfma_f32_16x16x32_bf16 v[40:43], v[170:173], v[40:43], v[68:71]
	s_nop 2
	s_and_saveexec_b64 s[4:5], s[74:75]
	s_cbranch_execz .LBB0_1091
	v_lshl_add_u32 v45, v89, 2, v79
	ds_write_b128 v45, v[48:51] offset:46080
	ds_write_b128 v45, v[52:55] offset:46144
	ds_write_b128 v45, v[56:59] offset:46208
	s_nop 0
	ds_write_b128 v45, v[40:43] offset:46272
	s_and_b64 exec, exec, s[68:69]
	v_add_f32_e32 v40, v76, v44
	ds_write_b32 v79, v40 offset:46336

; #define LAS __attribute__((address_space(3)))
; __device__ __forceinline__ bf16x8 mk8(s16x4 a, s16x4 b) { return __builtin_shufflevector(a, b, 0, 1, 2, 3, 4, 5, 6, 7); }
; #define MFMA16(a, b, c) __builtin_amdgcn_mfma_f32_16x16x32_bf16((a), (b), (c), 0, 0, 0)
; __device__ __forceinline__ s16x4 vtr(const LAS bf16_t* p) { return __builtin_bit_cast(s16x4, __builtin_amdgcn_ds_read_tr16_b64_v4i16((LAS v4i16_t*)p)); }
; __device__ __forceinline__ void sel_group(const LAS bf16_t* Kt, const LAS bf16_t* Vt, LAS float* S, const bf16x8 qB0, const bf16x8 qB1, int jc, int rc, bool valid, bool masked, int tw64, int lr, int q) {
;     ...
;     f32x4 ls = (f32x4){0.f, 0.f, 0.f, 0.f};
;     {
;         const LAS bf16_t* vbase = Vt + (4 * q + (lr >> 2)) * 72 + 4 * (lr & 3);
;         const bf16x8 ones = (bf16x8){0x3F80, 0x3F80, 0x3F80, 0x3F80, 0x3F80, 0x3F80, 0x3F80, 0x3F80};
;         s16x4 vv[2][2];
;         vv[0][0] = vtr(vbase); vv[0][1] = vtr(vbase + 16 * 72);
; #pragma unroll
;         for (int it = 0; it < 8; ++it) {
;             const int kk = it >> 2, dt = it & 3;
;             if (it < 7) { const int kk2 = (it + 1) >> 2, dt2 = (it + 1) & 3; vv[(it + 1) & 1][0] = vtr(vbase + (32 * kk2) * 72 + 16 * dt2); vv[(it + 1) & 1][1] = vtr(vbase + (32 * kk2 + 16) * 72 + 16 * dt2); }
;             __builtin_amdgcn_sched_barrier(0);
;             const bf16x8 vf = mk8(vv[it & 1][0], vv[it & 1][1]);
;             __builtin_amdgcn_s_setprio(1); acc[dt] = MFMA16(vf, pb[kk], acc[dt]);
;             if (dt == 0) ls = MFMA16(ones, pb[kk], ls);
;             __builtin_amdgcn_s_setprio(0);
;             __builtin_amdgcn_sched_barrier(0);
;         }
;     }
;     if (valid) {
; #pragma unroll
;         for (int dt = 0; dt < 4; ++dt) *(LAS f32x4*)(Srow + 16 * dt + 4 * q) = acc[dt];
;         if (q == 0) Srow[64] = lc + ls[0];
;     }
.LBB0_1102:
	s_mov_b32 s18, s16
	s_mov_b32 s19, s16
	s_mov_b32 s17, s16
	v_mov_b64_e32 v[58:59], s[18:19]
	v_mov_b64_e32 v[56:57], s[16:17]
	s_waitcnt lgkmcnt(0)
	v_mfma_f32_16x16x32_bf16 v[52:55], v[142:145], v[36:39], v[52:55]
	s_nop 0
	v_mfma_f32_16x16x32_bf16 v[64:67], v[56:59], v[36:39], 0
	v_mfma_f32_16x16x32_bf16 v[48:51], v[146:149], v[36:39], v[48:51]
	v_mfma_f32_16x16x32_bf16 v[72:75], v[150:153], v[36:39], v[44:47]
	v_mfma_f32_16x16x32_bf16 v[60:63], v[154:157], v[36:39], v[40:43]
	v_mfma_f32_16x16x32_bf16 v[40:43], v[158:161], v[32:35], v[52:55]
	v_mfma_f32_16x16x32_bf16 v[36:39], v[56:59], v[32:35], v[64:67]
	v_mfma_f32_16x16x32_bf16 v[44:47], v[162:165], v[32:35], v[48:51]
	v_mfma_f32_16x16x32_bf16 v[48:51], v[166:169], v[32:35], v[72:75]
	v_mfma_f32_16x16x32_bf16 v[32:35], v[170:173], v[32:35], v[60:63]
	s_nop 2
	s_and_saveexec_b64 s[4:5], s[70:71]
	s_cbranch_execz .LBB0_1056
	v_lshl_add_u32 v37, v89, 2, v71
	ds_write_b128 v37, v[40:43] offset:46080
	ds_write_b128 v37, v[44:47] offset:46144
	ds_write_b128 v37, v[48:51] offset:46208
	s_nop 0
	ds_write_b128 v37, v[32:35] offset:46272
	s_and_b64 exec, exec, s[68:69]
	s_cbranch_execz .LBB0_1056
	v_add_f32_e32 v32, v68, v36
	ds_write_b32 v71, v32 offset:46336
	s_branch .LBB0_1056
